# GEMM mainloop: LDS-DMA via scalar base + 32-bit lane offset (removes 16 v_lshl_add_u64 + 4 v_add per iteration), B-fragment ds_reads from pre-offset base
# speedup vs baseline: 1.0067x; 1.0031x over previous
.LBB0_260:
	s_lshr_b32 s78, s12, 6
	s_waitcnt vmcnt(0)
	v_bfe_u32 v10, v0, 4, 2
	s_and_b64 s[12:13], s[0:1], exec
	v_and_b32_e32 v191, 15, v0
	s_movk_i32 s12, 0x80
	v_lshlrev_b32_e32 v11, 4, v10
	v_lshlrev_b32_e32 v0, 2, v0
	s_cselect_b32 s79, s12, 0x8000
	s_lshl_b32 s13, s17, 6
	v_lshl_or_b32 v11, v191, 6, v11
	s_lshl_b32 s17, s17, 13
	v_and_b32_e32 v0, 32, v0
	v_bitop3_b32 v12, v11, s17, v0 bitop3:0xde
	s_lshl_b32 s17, s25, 5
	s_and_b32 s25, s17, 0x60
	s_add_i32 m0, s7, 0x18000
	v_lshl_add_u64 v[2:3], v[2:3], 0, s[48:49]
	s_lshl_b32 s17, s25, 7
	s_waitcnt vmcnt(2)
	s_barrier
	global_load_lds_dwordx4 v[2:3], off
	s_add_i32 m0, s7, 0x1a000
	s_add_u32 s40, s10, s79
	v_mov_b32_e32 v193, v1
	v_lshl_add_u64 v[2:3], v[4:5], 0, s[48:49]
	s_addc_u32 s41, s11, 0
	s_add_i32 s26, s7, 0x8000
	v_mov_b32_e32 v197, v1
	global_load_lds_dwordx4 v[2:3], off
	v_lshl_add_u64 v[2:3], s[40:41], 0, v[192:193]
	s_mov_b32 m0, s26
	s_add_i32 s36, s7, 0xa000
	global_load_lds_dwordx4 v[2:3], off
	v_lshl_add_u64 v[2:3], s[40:41], 0, v[196:197]
	s_mov_b32 m0, s36
	s_mov_b32 s12, 0
	global_load_lds_dwordx4 v[2:3], off
	s_add_i32 m0, s7, 0x1c000
	v_lshl_add_u64 v[2:3], v[6:7], 0, s[48:49]
	global_load_lds_dwordx4 v[2:3], off
	v_lshl_add_u64 v[2:3], v[8:9], 0, s[48:49]
	s_add_i32 m0, s7, 0x1e000
	s_and_b64 s[0:1], s[0:1], exec
	global_load_lds_dwordx4 v[2:3], off
	s_waitcnt vmcnt(6)
	s_cselect_b32 s76, 7, 15
	s_cmpk_lt_u32 s18, 0x100
	s_cselect_b64 s[80:81], -1, 0
	s_and_b64 s[34:35], s[34:35], exec
	v_lshlrev_b32_e32 v220, 3, v10
	v_bitop3_b32 v221, v11, s17, v0 bitop3:0xde
	v_add_u32_e32 v246, 0x10000, v221
	v_cmp_eq_u32_e64 s[0:1], 0, v10
	s_cselect_b32 s77, 22, 20
	s_add_u32 s98, s78, -2
	v_add_u32_e32 v222, 0, v12
	s_barrier
	s_branch .LBB0_263

.LBB0_272:
	s_add_u32 vcc_lo, s20, 1
	s_addc_u32 vcc_hi, s21, 0
	s_add_u32 s34, s20, 2
	s_addc_u32 s35, s21, 0
	s_lshl_b64 s[40:41], s[34:35], s76
	s_add_u32 s21, s10, s40
	s_addc_u32 s40, s11, s41
	s_cmp_eq_u32 s98, s20
	s_cselect_b32 s41, s17, s40
	s_cselect_b32 s40, s18, s21
	s_cselect_b32 s72, s53, s83
	s_cselect_b32 s73, s52, s85
	s_add_u32 s20, s40, s79
	s_addc_u32 s21, s41, 0
	s_add_i32 s99, 0, 0x10000
	s_add_i32 s24, 0, 0x14000
	s_waitcnt lgkmcnt(0)
	ds_read_b128 v[130:133], v246
	ds_read_b128 v[134:137], v246 offset:1024
	ds_read_b128 v[138:141], v246 offset:2048
	ds_read_b128 v[142:145], v246 offset:3072
	ds_read_b128 v[146:149], v246 offset:16384
	ds_read_b128 v[150:153], v246 offset:17408
	ds_read_b128 v[154:157], v246 offset:18432
	ds_read_b128 v[158:161], v246 offset:19456
	s_lshl_b64 vcc, vcc, s76
	s_add_u32 vcc_lo, s56, vcc_lo
	s_addc_u32 vcc_hi, s57, vcc_hi
	s_add_i32 m0, s7, 0xc000
	ds_read_b128 v[162:165], v222
	ds_read_b128 v[166:169], v222 offset:1024
	ds_read_b128 v[170:173], v222 offset:2048
	ds_read_b128 v[174:177], v222 offset:3072
	ds_read_b128 v[178:181], v222 offset:4096
	ds_read_b128 v[182:185], v222 offset:5120
	ds_read_b128 v[186:189], v222 offset:6144
	ds_read_b128 v[200:203], v222 offset:7168
	global_load_lds_dwordx4 v192, vcc
	s_add_i32 m0, s7, 0xe000
	s_nop 0
	global_load_lds_dwordx4 v196, vcc
	s_waitcnt vmcnt(8)
	s_waitcnt lgkmcnt(0)
	s_barrier
	s_setprio 1
	s_waitcnt lgkmcnt(0)
	v_mfma_f32_16x16x32_bf16 v[126:129], v[130:133], v[162:165], v[126:129]
	v_mfma_f32_16x16x32_bf16 v[122:125], v[138:141], v[162:165], v[122:125]
	v_mfma_f32_16x16x32_bf16 v[118:121], v[130:133], v[170:173], v[118:121]
	v_mfma_f32_16x16x32_bf16 v[114:117], v[138:141], v[170:173], v[114:117]
	v_mfma_f32_16x16x32_bf16 v[110:113], v[130:133], v[178:181], v[110:113]
	v_mfma_f32_16x16x32_bf16 v[106:109], v[138:141], v[178:181], v[106:109]
	v_mfma_f32_16x16x32_bf16 v[102:105], v[130:133], v[186:189], v[102:105]
	v_mfma_f32_16x16x32_bf16 v[98:101], v[138:141], v[186:189], v[98:101]
	v_mfma_f32_16x16x32_bf16 v[126:129], v[134:137], v[166:169], v[126:129]
	v_mfma_f32_16x16x32_bf16 v[122:125], v[142:145], v[166:169], v[122:125]
	v_mfma_f32_16x16x32_bf16 v[118:121], v[134:137], v[174:177], v[118:121]
	v_mfma_f32_16x16x32_bf16 v[114:117], v[142:145], v[174:177], v[114:117]
	v_mfma_f32_16x16x32_bf16 v[110:113], v[134:137], v[182:185], v[110:113]
	v_mfma_f32_16x16x32_bf16 v[106:109], v[142:145], v[182:185], v[106:109]
	v_mfma_f32_16x16x32_bf16 v[102:105], v[134:137], v[200:203], v[102:105]
	v_mfma_f32_16x16x32_bf16 v[98:101], v[142:145], v[200:203], v[98:101]
	s_setprio 0
	s_setprio 1
	v_mfma_f32_16x16x32_bf16 v[62:65], v[146:149], v[162:165], v[62:65]
	v_mfma_f32_16x16x32_bf16 v[58:61], v[154:157], v[162:165], v[58:61]
	v_mfma_f32_16x16x32_bf16 v[54:57], v[146:149], v[170:173], v[54:57]
	v_mfma_f32_16x16x32_bf16 v[50:53], v[154:157], v[170:173], v[50:53]
	v_mfma_f32_16x16x32_bf16 v[46:49], v[146:149], v[178:181], v[46:49]
	v_mfma_f32_16x16x32_bf16 v[42:45], v[154:157], v[178:181], v[42:45]
	v_mfma_f32_16x16x32_bf16 v[38:41], v[146:149], v[186:189], v[38:41]
	v_mfma_f32_16x16x32_bf16 v[34:37], v[154:157], v[186:189], v[34:37]
	v_mfma_f32_16x16x32_bf16 v[62:65], v[150:153], v[166:169], v[62:65]
	v_mfma_f32_16x16x32_bf16 v[58:61], v[158:161], v[166:169], v[58:61]
	v_mfma_f32_16x16x32_bf16 v[54:57], v[150:153], v[174:177], v[54:57]
	v_mfma_f32_16x16x32_bf16 v[50:53], v[158:161], v[174:177], v[50:53]
	v_mfma_f32_16x16x32_bf16 v[46:49], v[150:153], v[182:185], v[46:49]
	v_mfma_f32_16x16x32_bf16 v[42:45], v[158:161], v[182:185], v[42:45]
	v_mfma_f32_16x16x32_bf16 v[38:41], v[150:153], v[200:203], v[38:41]
	v_mfma_f32_16x16x32_bf16 v[34:37], v[158:161], v[200:203], v[34:37]
	s_setprio 0
	s_barrier
	s_add_i32 s99, s99, s6
	s_mov_b32 m0, s99
	ds_read_b128 v[162:165], v222 offset:16384
	ds_read_b128 v[166:169], v222 offset:17408
	ds_read_b128 v[170:173], v222 offset:18432
	ds_read_b128 v[174:177], v222 offset:19456
	ds_read_b128 v[178:181], v222 offset:20480
	ds_read_b128 v[182:185], v222 offset:21504
	ds_read_b128 v[186:189], v222 offset:22528
	ds_read_b128 v[200:203], v222 offset:23552
	global_load_lds_dwordx4 v194, s[72:73]
	s_add_i32 m0, s99, 0x2000
	s_mov_b64 vcc, s[72:73]
	s_add_u32 s72, s72, s58
	s_addc_u32 s73, s73, 0
	s_add_i32 s24, s24, s6
	global_load_lds_dwordx4 v198, vcc
	s_mov_b32 m0, s24
	s_nop 0
	global_load_lds_dwordx4 v194, s[72:73]
	s_add_i32 m0, s24, 0x2000
	s_nop 0
	global_load_lds_dwordx4 v198, s[72:73]
	s_mov_b32 m0, s7
	s_nop 0
	global_load_lds_dwordx4 v192, s[40:41]
	s_mov_b32 m0, s94
	s_nop 0
	global_load_lds_dwordx4 v196, s[40:41]
	s_waitcnt vmcnt(8)
	s_waitcnt lgkmcnt(0)
	s_barrier
	s_setprio 1
	s_waitcnt lgkmcnt(0)
	v_mfma_f32_16x16x32_bf16 v[94:97], v[130:133], v[162:165], v[94:97]
	v_mfma_f32_16x16x32_bf16 v[90:93], v[138:141], v[162:165], v[90:93]
	v_mfma_f32_16x16x32_bf16 v[86:89], v[130:133], v[170:173], v[86:89]
	v_mfma_f32_16x16x32_bf16 v[82:85], v[138:141], v[170:173], v[82:85]
	v_mfma_f32_16x16x32_bf16 v[78:81], v[130:133], v[178:181], v[78:81]
	v_mfma_f32_16x16x32_bf16 v[74:77], v[138:141], v[178:181], v[74:77]
	v_mfma_f32_16x16x32_bf16 v[70:73], v[130:133], v[186:189], v[70:73]
	v_mfma_f32_16x16x32_bf16 v[66:69], v[138:141], v[186:189], v[66:69]
	v_mfma_f32_16x16x32_bf16 v[94:97], v[134:137], v[166:169], v[94:97]
	v_mfma_f32_16x16x32_bf16 v[90:93], v[142:145], v[166:169], v[90:93]
	v_mfma_f32_16x16x32_bf16 v[86:89], v[134:137], v[174:177], v[86:89]
	v_mfma_f32_16x16x32_bf16 v[82:85], v[142:145], v[174:177], v[82:85]
	v_mfma_f32_16x16x32_bf16 v[78:81], v[134:137], v[182:185], v[78:81]
	v_mfma_f32_16x16x32_bf16 v[74:77], v[142:145], v[182:185], v[74:77]
	v_mfma_f32_16x16x32_bf16 v[70:73], v[134:137], v[200:203], v[70:73]
	v_mfma_f32_16x16x32_bf16 v[66:69], v[142:145], v[200:203], v[66:69]
	s_setprio 0
	s_setprio 1
	v_mfma_f32_16x16x32_bf16 v[30:33], v[146:149], v[162:165], v[30:33]
	v_mfma_f32_16x16x32_bf16 v[26:29], v[154:157], v[162:165], v[26:29]
	v_mfma_f32_16x16x32_bf16 v[22:25], v[146:149], v[170:173], v[22:25]
	v_mfma_f32_16x16x32_bf16 v[18:21], v[154:157], v[170:173], v[18:21]
	v_mfma_f32_16x16x32_bf16 v[14:17], v[146:149], v[178:181], v[14:17]
	v_mfma_f32_16x16x32_bf16 v[10:13], v[154:157], v[178:181], v[10:13]
	v_mfma_f32_16x16x32_bf16 v[6:9], v[146:149], v[186:189], v[6:9]
	v_mfma_f32_16x16x32_bf16 v[2:5], v[154:157], v[186:189], v[2:5]
	v_mfma_f32_16x16x32_bf16 v[30:33], v[150:153], v[166:169], v[30:33]
	v_mfma_f32_16x16x32_bf16 v[26:29], v[158:161], v[166:169], v[26:29]
	v_mfma_f32_16x16x32_bf16 v[22:25], v[150:153], v[174:177], v[22:25]
	v_mfma_f32_16x16x32_bf16 v[18:21], v[158:161], v[174:177], v[18:21]
	v_mfma_f32_16x16x32_bf16 v[14:17], v[150:153], v[182:185], v[14:17]
	v_mfma_f32_16x16x32_bf16 v[10:13], v[158:161], v[182:185], v[10:13]
	v_mfma_f32_16x16x32_bf16 v[6:9], v[150:153], v[200:203], v[6:9]
	v_mfma_f32_16x16x32_bf16 v[2:5], v[158:161], v[200:203], v[2:5]
	s_setprio 0
	s_barrier
	s_add_i32 s24, 0, 0x18000
	ds_read_b128 v[130:133], v246 offset:32768
	ds_read_b128 v[134:137], v246 offset:33792
	ds_read_b128 v[138:141], v246 offset:34816
	ds_read_b128 v[142:145], v246 offset:35840
	ds_read_b128 v[146:149], v246 offset:49152
	ds_read_b128 v[150:153], v246 offset:50176
	ds_read_b128 v[154:157], v246 offset:51200
	ds_read_b128 v[158:161], v246 offset:52224
	s_add_u32 s40, s40, s93
	s_addc_u32 s41, s41, s59
	s_mov_b32 m0, s95
	ds_read_b128 v[162:165], v222 offset:32768
	ds_read_b128 v[166:169], v222 offset:33792
	ds_read_b128 v[170:173], v222 offset:34816
	ds_read_b128 v[174:177], v222 offset:35840
	ds_read_b128 v[178:181], v222 offset:36864
	ds_read_b128 v[182:185], v222 offset:37888
	ds_read_b128 v[186:189], v222 offset:38912
	ds_read_b128 v[200:203], v222 offset:39936
	global_load_lds_dwordx4 v192, s[40:41]
	s_mov_b32 m0, s9
	s_nop 0
	global_load_lds_dwordx4 v196, s[40:41]
	s_waitcnt vmcnt(8)
	s_waitcnt lgkmcnt(0)
	s_barrier
	s_setprio 1
	s_waitcnt lgkmcnt(0)
	v_mfma_f32_16x16x32_bf16 v[126:129], v[130:133], v[162:165], v[126:129]
	v_mfma_f32_16x16x32_bf16 v[122:125], v[138:141], v[162:165], v[122:125]
	v_mfma_f32_16x16x32_bf16 v[118:121], v[130:133], v[170:173], v[118:121]
	v_mfma_f32_16x16x32_bf16 v[114:117], v[138:141], v[170:173], v[114:117]
	v_mfma_f32_16x16x32_bf16 v[110:113], v[130:133], v[178:181], v[110:113]
	v_mfma_f32_16x16x32_bf16 v[106:109], v[138:141], v[178:181], v[106:109]
	v_mfma_f32_16x16x32_bf16 v[102:105], v[130:133], v[186:189], v[102:105]
	v_mfma_f32_16x16x32_bf16 v[98:101], v[138:141], v[186:189], v[98:101]
	v_mfma_f32_16x16x32_bf16 v[126:129], v[134:137], v[166:169], v[126:129]
	v_mfma_f32_16x16x32_bf16 v[122:125], v[142:145], v[166:169], v[122:125]
	v_mfma_f32_16x16x32_bf16 v[118:121], v[134:137], v[174:177], v[118:121]
	v_mfma_f32_16x16x32_bf16 v[114:117], v[142:145], v[174:177], v[114:117]
	v_mfma_f32_16x16x32_bf16 v[110:113], v[134:137], v[182:185], v[110:113]
	v_mfma_f32_16x16x32_bf16 v[106:109], v[142:145], v[182:185], v[106:109]
	v_mfma_f32_16x16x32_bf16 v[102:105], v[134:137], v[200:203], v[102:105]
	v_mfma_f32_16x16x32_bf16 v[98:101], v[142:145], v[200:203], v[98:101]
	s_setprio 0
	s_setprio 1
	v_mfma_f32_16x16x32_bf16 v[62:65], v[146:149], v[162:165], v[62:65]
	v_mfma_f32_16x16x32_bf16 v[58:61], v[154:157], v[162:165], v[58:61]
	v_mfma_f32_16x16x32_bf16 v[54:57], v[146:149], v[170:173], v[54:57]
	v_mfma_f32_16x16x32_bf16 v[50:53], v[154:157], v[170:173], v[50:53]
	v_mfma_f32_16x16x32_bf16 v[46:49], v[146:149], v[178:181], v[46:49]
	v_mfma_f32_16x16x32_bf16 v[42:45], v[154:157], v[178:181], v[42:45]
	v_mfma_f32_16x16x32_bf16 v[38:41], v[146:149], v[186:189], v[38:41]
	v_mfma_f32_16x16x32_bf16 v[34:37], v[154:157], v[186:189], v[34:37]
	v_mfma_f32_16x16x32_bf16 v[62:65], v[150:153], v[166:169], v[62:65]
	v_mfma_f32_16x16x32_bf16 v[58:61], v[158:161], v[166:169], v[58:61]
	v_mfma_f32_16x16x32_bf16 v[54:57], v[150:153], v[174:177], v[54:57]
	v_mfma_f32_16x16x32_bf16 v[50:53], v[158:161], v[174:177], v[50:53]
	v_mfma_f32_16x16x32_bf16 v[46:49], v[150:153], v[182:185], v[46:49]
	v_mfma_f32_16x16x32_bf16 v[42:45], v[158:161], v[182:185], v[42:45]
	v_mfma_f32_16x16x32_bf16 v[38:41], v[150:153], v[200:203], v[38:41]
	v_mfma_f32_16x16x32_bf16 v[34:37], v[158:161], v[200:203], v[34:37]
	s_setprio 0
	s_barrier
	s_add_i32 s24, s24, s6
	s_add_i32 m0, s24, 0xffffff80
	ds_read_b128 v[162:165], v222 offset:49152
	ds_read_b128 v[166:169], v222 offset:50176
	ds_read_b128 v[170:173], v222 offset:51200
	ds_read_b128 v[174:177], v222 offset:52224
	ds_read_b128 v[178:181], v222 offset:53248
	ds_read_b128 v[182:185], v222 offset:54272
	ds_read_b128 v[186:189], v222 offset:55296
	ds_read_b128 v[200:203], v222 offset:56320
	global_load_lds_dwordx4 v194, vcc offset:128
	s_add_i32 m0, s24, 0x1f80
	s_add_i32 s24, s6, 0x1c000
	global_load_lds_dwordx4 v198, vcc offset:128
	s_add_i32 m0, s24, 0xffffff80
	s_nop 0
	global_load_lds_dwordx4 v194, s[72:73] offset:128
	s_add_i32 m0, s24, 0x1f80
	s_nop 0
	global_load_lds_dwordx4 v198, s[72:73] offset:128
	s_mov_b32 m0, s26
	s_nop 0
	global_load_lds_dwordx4 v192, s[20:21]
	s_mov_b32 m0, s36
	s_nop 0
	global_load_lds_dwordx4 v196, s[20:21]
	s_waitcnt vmcnt(8)
	s_waitcnt lgkmcnt(0)
	s_barrier
	s_setprio 1
	s_waitcnt lgkmcnt(0)
	v_mfma_f32_16x16x32_bf16 v[94:97], v[130:133], v[162:165], v[94:97]
	v_mfma_f32_16x16x32_bf16 v[90:93], v[138:141], v[162:165], v[90:93]
	v_mfma_f32_16x16x32_bf16 v[86:89], v[130:133], v[170:173], v[86:89]
	v_mfma_f32_16x16x32_bf16 v[82:85], v[138:141], v[170:173], v[82:85]
	v_mfma_f32_16x16x32_bf16 v[78:81], v[130:133], v[178:181], v[78:81]
	v_mfma_f32_16x16x32_bf16 v[74:77], v[138:141], v[178:181], v[74:77]
	v_mfma_f32_16x16x32_bf16 v[70:73], v[130:133], v[186:189], v[70:73]
	v_mfma_f32_16x16x32_bf16 v[66:69], v[138:141], v[186:189], v[66:69]
	v_mfma_f32_16x16x32_bf16 v[94:97], v[134:137], v[166:169], v[94:97]
	v_mfma_f32_16x16x32_bf16 v[90:93], v[142:145], v[166:169], v[90:93]
	v_mfma_f32_16x16x32_bf16 v[86:89], v[134:137], v[174:177], v[86:89]
	v_mfma_f32_16x16x32_bf16 v[82:85], v[142:145], v[174:177], v[82:85]
	v_mfma_f32_16x16x32_bf16 v[78:81], v[134:137], v[182:185], v[78:81]
	v_mfma_f32_16x16x32_bf16 v[74:77], v[142:145], v[182:185], v[74:77]
	v_mfma_f32_16x16x32_bf16 v[70:73], v[134:137], v[200:203], v[70:73]
	v_mfma_f32_16x16x32_bf16 v[66:69], v[142:145], v[200:203], v[66:69]
	s_setprio 0
	s_setprio 1
	v_mfma_f32_16x16x32_bf16 v[30:33], v[146:149], v[162:165], v[30:33]
	v_mfma_f32_16x16x32_bf16 v[26:29], v[154:157], v[162:165], v[26:29]
	v_mfma_f32_16x16x32_bf16 v[22:25], v[146:149], v[170:173], v[22:25]
	v_mfma_f32_16x16x32_bf16 v[18:21], v[154:157], v[170:173], v[18:21]
	v_mfma_f32_16x16x32_bf16 v[14:17], v[146:149], v[178:181], v[14:17]
	v_mfma_f32_16x16x32_bf16 v[10:13], v[154:157], v[178:181], v[10:13]
	v_mfma_f32_16x16x32_bf16 v[6:9], v[146:149], v[186:189], v[6:9]
	v_mfma_f32_16x16x32_bf16 v[2:5], v[154:157], v[186:189], v[2:5]
	v_mfma_f32_16x16x32_bf16 v[30:33], v[150:153], v[166:169], v[30:33]
	v_mfma_f32_16x16x32_bf16 v[26:29], v[158:161], v[166:169], v[26:29]
	v_mfma_f32_16x16x32_bf16 v[22:25], v[150:153], v[174:177], v[22:25]
	v_mfma_f32_16x16x32_bf16 v[18:21], v[158:161], v[174:177], v[18:21]
	v_mfma_f32_16x16x32_bf16 v[14:17], v[150:153], v[182:185], v[14:17]
	v_mfma_f32_16x16x32_bf16 v[10:13], v[158:161], v[182:185], v[10:13]
	v_mfma_f32_16x16x32_bf16 v[6:9], v[150:153], v[200:203], v[6:9]
	v_mfma_f32_16x16x32_bf16 v[2:5], v[158:161], v[200:203], v[2:5]
	s_setprio 0
	s_barrier
	s_add_u32 s83, s83, 0x100
	s_addc_u32 s85, s85, 0
	s_cmp_ge_u32 s34, s78
	s_mov_b64 s[20:21], s[34:35]
	s_cbranch_scc0 .LBB0_272
	s_and_b64 vcc, exec, s[80:81]
	s_cbranch_vccz .LBB0_275
	s_barrier
